# diff-attention tile loop unrolled x2 with a second K/V staging set in borrowed constant VGPRs (restored after the mixer): global prefetch distance 2 tiles
# baseline (speedup 1.0000x reference)
; #define ALAS __attribute__((address_space(3)))
; __device__ __forceinline__ void diff_unit(int b, int hd, int qb, const bf16_t* Q, const bf16_t* K, const bf16_t* VT, bf16_t* O, const float* biasd, float lam, const float* subg, ALAS unsigned char* lds) {
;     ...
;     for (int t = 0; t < NT; ++t) {
;         ALAS unsigned char* buf = lds + (t & 1) * 36864;
; #pragma unroll
;         for (int i = 0; i < 2; ++i) { *(ALAS u32x4*)(buf + kl[i]) = kr[i]; *(ALAS u32x4*)(buf + vl[i]) = vr[i]; }
;         __syncthreads();
;         if (t + 1 < NT) {
; #pragma unroll
;             for (int i = 0; i < 2; ++i) { kr[i] = *(const u32x4*)(kg[i] + (size_t)(t + 1) * 64 * 1024); vr[i] = *(const u32x4*)(vg[i] + (t + 1) * 64); }
;         }
.LBB0_502:
	s_lshr_b32 s17, s1, 2
	s_lshl_b32 s4, s0, 11
	s_and_b32 s4, s4, 0x3800000
	s_and_b32 s17, s17, 7
	v_lshlrev_b64 v[64:65], 11, v[64:65]
	s_lshl_b32 s17, s17, 8
	v_lshl_add_u64 v[64:65], s[4:5], 0, v[64:65]
	v_readlane_b32 s36, v255, 20
	v_or3_b32 v64, v64, s17, v144
	v_readlane_b32 s37, v255, 21
	s_lshl_b32 s18, s14, 1
	s_add_i32 s12, s12, s13
	v_lshl_add_u64 v[164:165], s[36:37], 0, v[64:65]
	v_lshlrev_b64 v[64:65], 11, v[66:67]
	v_lshl_add_u64 v[64:65], s[4:5], 0, v[64:65]
	v_or3_b32 v64, v64, s17, v144
	s_or_b32 s15, s15, 31
	s_mov_b32 s14, 2
	s_add_i32 s16, s18, 2
	v_mov_b32_e32 v131, v136
	s_addk_i32 s12, 0xff81
	v_sub_u32_e32 v159, v70, v134
	v_lshl_add_u64 v[166:167], s[36:37], 0, v[64:65]
	s_not_b32 s13, s18
	s_mov_b32 s17, 64
	s_cmp_lt_i32 s16, 3
	s_cbranch_scc1 .Ldf_nopre
	global_load_dwordx4 v[146:149], v[164:165], off
	global_load_dwordx4 v[208:211], v[166:167], off
	global_load_dwordx4 v[150:153], v[140:141], off offset:256
	global_load_dwordx2 v[154:155], v[156:157], off offset:256
	global_load_dwordx2 v[212:213], v[156:157], off offset:264
	v_lshl_add_u64 v[164:165], v[164:165], 0, s[30:31]
	v_lshl_add_u64 v[166:167], v[166:167], 0, s[30:31]
.Ldf_nopre:
	s_branch .LBB0_504

; #define ALAS __attribute__((address_space(3)))
; __device__ __forceinline__ void diff_unit(int b, int hd, int qb, const bf16_t* Q, const bf16_t* K, const bf16_t* VT, bf16_t* O, const float* biasd, float lam, const float* subg, ALAS unsigned char* lds) {
;     ...
;     for (int t = 0; t < NT; ++t) {
;         ALAS unsigned char* buf = lds + (t & 1) * 36864;
; #pragma unroll
;         for (int i = 0; i < 2; ++i) { *(ALAS u32x4*)(buf + kl[i]) = kr[i]; *(ALAS u32x4*)(buf + vl[i]) = vr[i]; }
;         __syncthreads();
;         if (t + 1 < NT) {
; #pragma unroll
;             for (int i = 0; i < 2; ++i) { kr[i] = *(const u32x4*)(kg[i] + (size_t)(t + 1) * 64 * 1024); vr[i] = *(const u32x4*)(vg[i] + (t + 1) * 64); }
;         }
.Ldf_504b:
	s_bitcmp1_b32 s14, 0
	s_cselect_b32 s4, 0, 0x9000
	s_add_i32 s18, s4, 0
	s_cmp_lt_i32 s14, s16
	s_cbranch_scc1 .Ldf_wnextb
	s_waitcnt vmcnt(0)
	s_branch .Ldf_wgob
.Ldf_wnextb:
	s_waitcnt vmcnt(4)
.Ldf_wgob:
	v_add_u32_e32 v64, s18, v138
	ds_write_b128 v64, v[146:149]
	v_add_u32_e32 v64, s18, v158
	ds_write_b128 v64, v[150:153] offset:18432
	v_add_u32_e32 v64, s18, v142
	ds_write_b128 v64, v[208:211]
	v_add_u32_e32 v64, s18, v160
	ds_write_b64 v64, v[154:155] offset:18432
	ds_write_b64 v64, v[212:213] offset:18440
	s_add_i32 s4, s14, 1
	s_cmp_ge_i32 s4, s16
	s_waitcnt lgkmcnt(0)
	s_barrier
	v_add_u32_e32 v144, s18, v139
	v_add3_u32 v144, s11, v144, v130
	ds_read_b128 v[172:175], v144 offset:0
	ds_read_b128 v[176:179], v144 offset:4608
	ds_read_b128 v[180:183], v144 offset:32
	ds_read_b128 v[184:187], v144 offset:4640
	ds_read_b128 v[188:191], v144 offset:64
	ds_read_b128 v[192:195], v144 offset:4672
	ds_read_b128 v[196:199], v144 offset:96
	ds_read_b128 v[216:219], v144 offset:4704
	s_cbranch_scc1 .Ldf_506b
	s_add_i32 s4, s17, 0x80
	s_lshl_b64 s[36:37], s[4:5], 1
	v_lshl_add_u64 v[64:65], v[156:157], 0, s[36:37]
	v_lshl_add_u64 v[66:67], v[140:141], 0, s[36:37]
	global_load_dwordx4 v[146:149], v[164:165], off
	global_load_dwordx4 v[208:211], v[166:167], off
	global_load_dwordx4 v[150:153], v[66:67], off
	global_load_dwordx2 v[154:155], v[64:65], off
	global_load_dwordx2 v[212:213], v[64:65], off offset:8

; #define ALAS __attribute__((address_space(3)))
; __device__ __forceinline__ float ex2(float x) { return __builtin_amdgcn_exp2f(x); }
; template <int NDB> __device__ __forceinline__ void wait_v(bf16x8 (&v)[2 * NDB]) { if constexpr (NDB == 4) lds_wait8(v); else lds_wait4(v); }
; template <int NDB>
; __device__ __forceinline__ void softmax_pv(f32x16& s0, f32x16& s1, float& mref, float& lsum, f32x16 (&o)[NDB], const ALAS unsigned char* Vb, int r32, int hi) {
;     const unsigned vp = (unsigned)(uintptr_t)(Vb + r32 * ROWB + hi * 16);
;     bf16x8 va[2 * NDB], vb[2 * NDB];
;     issue_v<NDB, 0>(va, vp);
;     float ps = 0.f;
; #pragma unroll
;     for (int r = 0; r < 16; ++r) { s0[r] = ex2(s0[r]); ps += s0[r]; }
;     bf16x8 pf0, pf1, pf2, pf3;
;     pack16(s0, pf0, pf1);
;     wait_v<NDB>(va);
;     issue_v<NDB, 1>(vb, vp);
;     __builtin_amdgcn_sched_barrier(0);
; #pragma unroll
;     for (int d = 0; d < NDB; ++d) o[d] = __builtin_amdgcn_mfma_f32_32x32x16_bf16(va[d], pf0, o[d], 0, 0, 0);
; #pragma unroll
;     for (int d = 0; d < NDB; ++d) o[d] = __builtin_amdgcn_mfma_f32_32x32x16_bf16(va[NDB + d], pf1, o[d], 0, 0, 0);
; #pragma unroll
;     for (int r = 0; r < 16; ++r) { s1[r] = ex2(s1[r]); ps += s1[r]; }
;     pack16(s1, pf2, pf3);
; #pragma unroll
;     for (int i = 0; i < 2 * NDB; ++i) { __builtin_amdgcn_sched_group_barrier(0x008, 1, 0); __builtin_amdgcn_sched_group_barrier(0x002, (NDB == 4 ? 5 : 10), 0); }
;     __builtin_amdgcn_sched_barrier(0);
;     wait_v<NDB>(vb);
;     __builtin_amdgcn_sched_barrier(0);
; #pragma unroll
;     for (int d = 0; d < NDB; ++d) o[d] = __builtin_amdgcn_mfma_f32_32x32x16_bf16(vb[d], pf2, o[d], 0, 0, 0);
; #pragma unroll
;     for (int d = 0; d < NDB; ++d) o[d] = __builtin_amdgcn_mfma_f32_32x32x16_bf16(vb[NDB + d], pf3, o[d], 0, 0, 0);
;     lsum += ps;
;     if (__any(ps > 1048576.0f)) {
;         const float pt = ps + __shfl_xor(ps, 32); const float dl = pt > 1048576.0f ? floorf(__log2f(pt)) : 0.f, al = ex2(-dl); mref += dl; lsum *= al;
; #pragma unroll
;         for (int d = 0; d < NDB; ++d)
; #pragma unroll
;             for (int r = 0; r < 16; ++r) o[d][r] *= al;
;     }
; }
.Ldf_509b:
	v_add_u32_e32 v144, s18, v143
	v_add3_u32 v144, v144, v130, s35
	ds_read_b128 v[172:175], v144 offset:0
	ds_read_b128 v[176:179], v144 offset:4608
	ds_read_b128 v[180:183], v144 offset:9216
	ds_read_b128 v[184:187], v144 offset:13824
	ds_read_b128 v[188:191], v144 offset:32
	ds_read_b128 v[192:195], v144 offset:4640
	ds_read_b128 v[196:199], v144 offset:9248
	ds_read_b128 v[216:219], v144 offset:13856
	s_nop 7
	v_exp_f32_e32 v248, v88
	v_exp_f32_e32 v249, v89
	v_exp_f32_e32 v250, v90
	v_exp_f32_e32 v251, v91
	ds_read_b128 v[88:91], v144 offset:64
	v_exp_f32_e32 v252, v92
	v_exp_f32_e32 v253, v93
	v_exp_f32_e32 v215, v94
	v_exp_f32_e32 v207, v95
	ds_read_b128 v[92:95], v144 offset:4672
	ds_read_b128 v[220:223], v144 offset:9280
	ds_read_b128 v[224:227], v144 offset:13888
	ds_read_b128 v[228:231], v144 offset:96
	ds_read_b128 v[232:235], v144 offset:4704
	v_exp_f32_e32 v161, v80
	v_exp_f32_e32 v168, v81
	v_exp_f32_e32 v169, v82
	v_exp_f32_e32 v171, v83
	v_exp_f32_e32 v244, v84
	v_exp_f32_e32 v245, v85
	v_exp_f32_e32 v246, v86
	v_exp_f32_e32 v247, v87
	ds_read_b128 v[236:239], v144 offset:9312
	ds_read_b128 v[240:243], v144 offset:13920
	v_cvt_pk_bf16_f32 v80, v161, v168
	v_cvt_pk_bf16_f32 v81, v169, v171
	v_cvt_pk_bf16_f32 v82, v244, v245
	v_cvt_pk_bf16_f32 v83, v246, v247
	v_cvt_pk_bf16_f32 v84, v248, v249
	v_cvt_pk_bf16_f32 v85, v250, v251
	v_cvt_pk_bf16_f32 v86, v252, v253
	v_cvt_pk_bf16_f32 v87, v215, v207
	s_waitcnt lgkmcnt(8)
	v_mfma_f32_32x32x16_bf16 v[48:63], v[172:175], v[80:83], v[48:63]
	v_add_f32_e32 v144, 0, v161
	v_add_f32_e32 v144, v168, v144
	v_add_f32_e32 v144, v169, v144
	v_add_f32_e32 v144, v171, v144
	v_add_f32_e32 v144, v244, v144
	v_exp_f32_e32 v161, v68
	v_exp_f32_e32 v168, v69
	v_mfma_f32_32x32x16_bf16 v[32:47], v[176:179], v[80:83], v[32:47]
	v_add_f32_e32 v144, v245, v144
	v_add_f32_e32 v144, v246, v144
	v_add_f32_e32 v144, v247, v144
	v_add_f32_e32 v144, v248, v144
	v_add_f32_e32 v144, v249, v144
	v_exp_f32_e32 v169, v70
	v_exp_f32_e32 v171, v71
	v_mfma_f32_32x32x16_bf16 v[16:31], v[180:183], v[80:83], v[16:31]
	v_add_f32_e32 v144, v250, v144
	v_add_f32_e32 v144, v251, v144
	v_add_f32_e32 v144, v252, v144
	v_add_f32_e32 v144, v253, v144
	v_add_f32_e32 v144, v215, v144
	v_exp_f32_e32 v72, v72
	v_exp_f32_e32 v73, v73
	v_mfma_f32_32x32x16_bf16 v[0:15], v[184:187], v[80:83], v[0:15]
	v_exp_f32_e32 v81, v64
	v_exp_f32_e32 v82, v65
	v_exp_f32_e32 v83, v66
	v_add_f32_e32 v80, v207, v144
	v_exp_f32_e32 v144, v67
	v_add_f32_e32 v80, v81, v80
	v_add_f32_e32 v80, v82, v80
	v_exp_f32_e32 v74, v74
	v_exp_f32_e32 v75, v75
	v_exp_f32_e32 v76, v76
	v_exp_f32_e32 v77, v77
	v_exp_f32_e32 v78, v78
	v_exp_f32_e32 v79, v79
	v_add_f32_e32 v80, v83, v80
	v_add_f32_e32 v80, v144, v80
	v_add_f32_e32 v80, v161, v80
	v_add_f32_e32 v80, v168, v80
	v_cvt_pk_bf16_f32 v64, v81, v82
	v_cvt_pk_bf16_f32 v65, v83, v144
	v_cvt_pk_bf16_f32 v66, v161, v168
	v_cvt_pk_bf16_f32 v67, v169, v171
	v_mfma_f32_32x32x16_bf16 v[48:63], v[188:191], v[84:87], v[48:63]
	v_cvt_pk_bf16_f32 v68, v72, v73
	v_cvt_pk_bf16_f32 v69, v74, v75
	v_cvt_pk_bf16_f32 v70, v76, v77
	v_cvt_pk_bf16_f32 v71, v78, v79
	v_add_f32_e32 v80, v169, v80
	v_add_f32_e32 v80, v171, v80
	v_add_f32_e32 v72, v72, v80
	v_mfma_f32_32x32x16_bf16 v[32:47], v[192:195], v[84:87], v[32:47]
	v_add_f32_e32 v72, v73, v72
	v_add_f32_e32 v72, v74, v72
	v_add_f32_e32 v72, v75, v72
	v_add_f32_e32 v72, v76, v72
	v_add_f32_e32 v72, v77, v72
	v_add_f32_e32 v72, v78, v72
	v_mfma_f32_32x32x16_bf16 v[16:31], v[196:199], v[84:87], v[16:31]
	v_mfma_f32_32x32x16_bf16 v[0:15], v[216:219], v[84:87], v[0:15]
	s_waitcnt lgkmcnt(0)
	s_nop 0
	v_mfma_f32_32x32x16_bf16 v[48:63], v[88:91], v[64:67], v[48:63]
	v_mfma_f32_32x32x16_bf16 v[32:47], v[92:95], v[64:67], v[32:47]
	v_mfma_f32_32x32x16_bf16 v[16:31], v[220:223], v[64:67], v[16:31]
	v_mfma_f32_32x32x16_bf16 v[0:15], v[224:227], v[64:67], v[0:15]
	v_add_f32_e32 v64, v79, v72
	v_add_f32_e32 v162, v162, v64
	v_cmp_lt_f32_e32 vcc, s34, v64
	v_mfma_f32_32x32x16_bf16 v[48:63], v[228:231], v[68:71], v[48:63]
	v_mfma_f32_32x32x16_bf16 v[32:47], v[232:235], v[68:71], v[32:47]
	v_mfma_f32_32x32x16_bf16 v[16:31], v[236:239], v[68:71], v[16:31]
	v_mfma_f32_32x32x16_bf16 v[0:15], v[240:243], v[68:71], v[0:15]
	s_cbranch_vccz .Ldf_503b
	ds_bpermute_b32 v65, v170, v64
	s_waitcnt lgkmcnt(0)
	v_add_f32_e32 v64, v64, v65
	v_log_f32_e32 v65, v64
	v_cmp_lt_f32_e32 vcc, s34, v64
	v_floor_f32_e32 v65, v65
	s_nop 0
	v_cndmask_b32_e32 v65, 0, v65, vcc
	v_exp_f32_e64 v64, -v65
	v_add_f32_e32 v163, v163, v65
	v_mul_f32_e32 v162, v162, v64
	v_pk_mul_f32 v[62:63], v[62:63], v[64:65] op_sel_hi:[1,0]
	v_pk_mul_f32 v[60:61], v[60:61], v[64:65] op_sel_hi:[1,0]
	v_pk_mul_f32 v[58:59], v[58:59], v[64:65] op_sel_hi:[1,0]
	v_pk_mul_f32 v[56:57], v[56:57], v[64:65] op_sel_hi:[1,0]
	v_pk_mul_f32 v[54:55], v[54:55], v[64:65] op_sel_hi:[1,0]
	v_pk_mul_f32 v[52:53], v[52:53], v[64:65] op_sel_hi:[1,0]
	v_pk_mul_f32 v[50:51], v[50:51], v[64:65] op_sel_hi:[1,0]
	v_pk_mul_f32 v[48:49], v[48:49], v[64:65] op_sel_hi:[1,0]
	v_pk_mul_f32 v[46:47], v[46:47], v[64:65] op_sel_hi:[1,0]
	v_pk_mul_f32 v[44:45], v[44:45], v[64:65] op_sel_hi:[1,0]
	v_pk_mul_f32 v[42:43], v[42:43], v[64:65] op_sel_hi:[1,0]
	v_pk_mul_f32 v[40:41], v[40:41], v[64:65] op_sel_hi:[1,0]
	v_pk_mul_f32 v[38:39], v[38:39], v[64:65] op_sel_hi:[1,0]
	v_pk_mul_f32 v[36:37], v[36:37], v[64:65] op_sel_hi:[1,0]
	v_pk_mul_f32 v[34:35], v[34:35], v[64:65] op_sel_hi:[1,0]
	v_pk_mul_f32 v[32:33], v[32:33], v[64:65] op_sel_hi:[1,0]
	v_pk_mul_f32 v[30:31], v[30:31], v[64:65] op_sel_hi:[1,0]
	v_pk_mul_f32 v[28:29], v[28:29], v[64:65] op_sel_hi:[1,0]
	v_pk_mul_f32 v[26:27], v[26:27], v[64:65] op_sel_hi:[1,0]
	v_pk_mul_f32 v[24:25], v[24:25], v[64:65] op_sel_hi:[1,0]
	v_pk_mul_f32 v[22:23], v[22:23], v[64:65] op_sel_hi:[1,0]
	v_pk_mul_f32 v[20:21], v[20:21], v[64:65] op_sel_hi:[1,0]
	v_pk_mul_f32 v[18:19], v[18:19], v[64:65] op_sel_hi:[1,0]
	v_pk_mul_f32 v[16:17], v[16:17], v[64:65] op_sel_hi:[1,0]
	v_pk_mul_f32 v[14:15], v[14:15], v[64:65] op_sel_hi:[1,0]
	v_pk_mul_f32 v[12:13], v[12:13], v[64:65] op_sel_hi:[1,0]
	v_pk_mul_f32 v[10:11], v[10:11], v[64:65] op_sel_hi:[1,0]
	v_pk_mul_f32 v[8:9], v[8:9], v[64:65] op_sel_hi:[1,0]
	v_pk_mul_f32 v[6:7], v[6:7], v[64:65] op_sel_hi:[1,0]
	v_pk_mul_f32 v[4:5], v[4:5], v[64:65] op_sel_hi:[1,0]
	v_pk_mul_f32 v[2:3], v[2:3], v[64:65] op_sel_hi:[1,0]
	v_pk_mul_f32 v[0:1], v[0:1], v[64:65] op_sel_hi:[1,0]
	s_branch .Ldf_503b
.Ldf_503b:
	s_add_i32 s14, s14, 1
	s_sub_i32 s12, s12, 64
	s_add_i32 s17, s17, 64
	s_add_i32 s4, s13, s14
	v_lshl_add_u64 v[164:165], v[164:165], 0, s[30:31]
	s_cmp_eq_u32 s4, 2
	v_lshl_add_u64 v[166:167], v[166:167], 0, s[30:31]
	s_cbranch_scc1 .LBB0_512

; #define ALAS __attribute__((address_space(3)))
; __device__ __forceinline__ void diff_unit(int b, int hd, int qb, const bf16_t* Q, const bf16_t* K, const bf16_t* VT, bf16_t* O, const float* biasd, float lam, const float* subg, ALAS unsigned char* lds) {
;     ...
;     for (int t = 0; t < NT; ++t) {
;         ALAS unsigned char* buf = lds + (t & 1) * 36864;
; #pragma unroll
;         for (int i = 0; i < 2; ++i) { *(ALAS u32x4*)(buf + kl[i]) = kr[i]; *(ALAS u32x4*)(buf + vl[i]) = vr[i]; }
;         __syncthreads();
;         if (t + 1 < NT) {
; #pragma unroll
;             for (int i = 0; i < 2; ++i) { kr[i] = *(const u32x4*)(kg[i] + (size_t)(t + 1) * 64 * 1024); vr[i] = *(const u32x4*)(vg[i] + (t + 1) * 64); }
;         }
.Ldf_wnext:
	s_waitcnt vmcnt(5)
.Ldf_wgo:
	v_add_u32_e32 v64, s18, v138
	ds_write_b128 v64, v[112:115]
	v_add_u32_e32 v64, s18, v158
	ds_write_b128 v64, v[116:119] offset:18432
	v_add_u32_e32 v64, s18, v142
	ds_write_b128 v64, v[120:123]
	v_add_u32_e32 v64, s18, v160
	ds_write_b128 v64, v[124:127] offset:18432
	s_add_i32 s4, s14, 1
	s_cmp_ge_i32 s4, s16
	s_waitcnt lgkmcnt(0)
	s_barrier
	v_add_u32_e32 v144, s18, v139
	v_add3_u32 v144, s11, v144, v130
	ds_read_b128 v[172:175], v144 offset:0
	ds_read_b128 v[176:179], v144 offset:4608
	ds_read_b128 v[180:183], v144 offset:32
	ds_read_b128 v[184:187], v144 offset:4640
	ds_read_b128 v[188:191], v144 offset:64
	ds_read_b128 v[192:195], v144 offset:4672
	ds_read_b128 v[196:199], v144 offset:96
	ds_read_b128 v[216:219], v144 offset:4704
	s_cbranch_scc1 .LBB0_506
	s_add_i32 s4, s17, 0x80
	s_lshl_b64 s[36:37], s[4:5], 1
	v_lshl_add_u64 v[64:65], v[156:157], 0, s[36:37]
	v_lshl_add_u64 v[66:67], v[140:141], 0, s[36:37]
	global_load_dwordx4 v[112:115], v[164:165], off
	global_load_dwordx4 v[120:123], v[166:167], off
	global_load_dwordx4 v[116:119], v[66:67], off
	global_load_dwordx4 v[124:127], v[64:65], off

; #define SEAM(k) do { if (IN(k) && IN((k) + 1)) { xcd_barrier(bar); } } while (0)
; __device__ __forceinline__ void xcd_barrier(const XcdBarrier& b) {
;     asm volatile("s_waitcnt vmcnt(0)" ::: "memory");
;     __syncthreads();
;     if (threadIdx.x == 0) {
;         unsigned* bar = b.bar;
;         __builtin_amdgcn_s_waitcnt(0);
;         unsigned nloc = b.st[0], nx = b.st[1];
;         if (nloc == 0u) { xcd_barrier_complete(bar, b.x, nloc, nx); b.st[0] = nloc; b.st[1] = nx; }
; __global__ void __launch_bounds__(512, 2) fwd_kernel(Params p) {
;     ...
;         SEAM(pb + 3);
;         if (IN(pb + 4)) { pg8::EpiResid<false> E{nullptr, XA, ss + (size_t)(3 * l + 2) * MTOK * 16, 1.0f}; run_gemm(lds, Ob, Wo, MTOK, 1024, 1024, E); }
.LBB0_546:
	v_mov_b64_e32 v[146:147], 0xb00
	v_mov_b64_e32 v[148:149], 0xaff
	v_mov_b64_e32 v[150:151], 0x200
	v_mov_b64_e32 v[152:153], 0x1ff
	v_mov_b64_e32 v[154:155], 0x3ff
	v_mov_b32_e32 v208, 0x100
	v_mov_b32_e32 v209, 0x200
	v_mov_b32_e32 v210, 0x400
	v_mov_b32_e32 v211, 0x800
	v_mov_b32_e32 v212, 0x1000
	v_mov_b32_e32 v213, 0x2000
	s_mul_i32 s0, s52, 7
	s_add_i32 s4, s0, 5
	s_cmp_lt_i32 s4, s90
	s_cselect_b64 s[0:1], -1, 0
	s_and_b64 s[6:7], s[28:29], s[0:1]
	s_andn2_b64 vcc, exec, s[6:7]
	s_cbranch_vccnz .LBB0_600
	s_waitcnt vmcnt(0)
	s_waitcnt lgkmcnt(0)
	s_barrier
	s_mov_b64 s[6:7], exec
	v_readlane_b32 s8, v254, 3
	v_readlane_b32 s9, v254, 4
	s_and_b64 s[8:9], s[6:7], s[8:9]
	s_mov_b64 exec, s[8:9]
	s_cbranch_execz .LBB0_599
	v_readlane_b32 s8, v255, 24
	s_waitcnt vmcnt(0) expcnt(0) lgkmcnt(0)
	s_nop 0
	v_mov_b32_e32 v0, s8
	ds_read_b32 v2, v0
	v_readlane_b32 s8, v255, 25
	s_waitcnt lgkmcnt(0)
	v_cmp_ne_u32_e32 vcc, 0, v2
	v_mov_b32_e32 v0, s8
	ds_read_b32 v0, v0
	s_cbranch_vccnz .LBB0_563
	s_mov_b32 s14, 1
	s_branch .LBB0_551
